# k56 with the readfirstlane wait states supplied + SwiGLU epilogue store addresses formed on the SALU (scalar running base + 32-bit lane offset)
# speedup vs baseline: 1.0024x; 1.0024x over previous
.Lepi_lead_448:
	v_mul_f32_e32 v0, v135, v232
	v_pk_mul_f32 v[126:127], v[0:1], v[126:127] op_sel_hi:[0,1]
	v_pk_mul_f32 v[128:129], v[0:1], v[128:129] op_sel_hi:[0,1]
	v_pk_mul_f32 v[124:125], v[0:1], v[124:125] op_sel_hi:[0,1]
	v_pk_mul_f32 v[122:123], v[0:1], v[122:123] op_sel_hi:[0,1]
	v_pk_mul_f32 v[214:215], v[126:127], s[100:101] op_sel_hi:[1,0]
	v_exp_f32_e32 v214, v214
	v_exp_f32_e32 v215, v215
	v_mul_f32_e32 v152, v135, v233
	v_pk_mul_f32 v[118:119], v[152:153], v[118:119] op_sel_hi:[0,1]
	v_pk_mul_f32 v[120:121], v[152:153], v[120:121] op_sel_hi:[0,1]
	v_pk_add_f32 v[214:215], v[214:215], 1.0 op_sel_hi:[1,0]
	v_rcp_f32_e32 v154, v214
	v_pk_mul_f32 v[114:115], v[152:153], v[114:115] op_sel_hi:[0,1]
	v_pk_mul_f32 v[116:117], v[152:153], v[116:117] op_sel_hi:[0,1]
	v_mad_i64_i32 v[152:153], s[24:25], v149, s52, v[130:131]
	s_lshl_b32 s98, s52, 4
	s_mul_i32 s99, s52, 0x50
	v_readfirstlane_b32 s24, v152
	v_readfirstlane_b32 s25, v153
	s_nop 1
	v_subrev_u32_e32 v152, s24, v152
	v_rcp_f32_e32 v155, v215
	v_pk_mul_f32 v[216:217], v[128:129], s[100:101] op_sel_hi:[1,0]
	v_exp_f32_e32 v216, v216
	v_exp_f32_e32 v217, v217
	v_cvt_f32_i32_e32 v43, v43
	v_pk_mul_f32 v[126:127], v[126:127], v[154:155]
	v_cvt_f32_i32_e32 v42, v42
	v_pk_add_f32 v[216:217], v[216:217], 1.0 op_sel_hi:[1,0]
	v_rcp_f32_e32 v156, v216
	v_pk_mul_f32 v[118:119], v[118:119], v[126:127]
	v_cvt_f32_i32_e32 v45, v45
	v_cvt_f32_i32_e32 v44, v44
	v_rcp_f32_e32 v157, v217
	v_pk_mul_f32 v[218:219], v[122:123], s[100:101] op_sel_hi:[1,0]
	v_exp_f32_e32 v218, v218
	v_exp_f32_e32 v219, v219
	v_cvt_f32_i32_e32 v53, v53
	v_pk_mul_f32 v[128:129], v[128:129], v[156:157]
	v_cvt_f32_i32_e32 v52, v52
	v_pk_add_f32 v[218:219], v[218:219], 1.0 op_sel_hi:[1,0]
	v_rcp_f32_e32 v126, v218
	v_pk_mul_f32 v[120:121], v[120:121], v[128:129]
	v_cvt_f32_i32_e32 v51, v51
	v_cvt_f32_i32_e32 v50, v50
	v_rcp_f32_e32 v127, v219
	v_pk_mul_f32 v[220:221], v[124:125], s[100:101] op_sel_hi:[1,0]
	v_exp_f32_e32 v220, v220
	v_exp_f32_e32 v221, v221
	v_cvt_f32_i32_e32 v39, v39
	v_pk_mul_f32 v[122:123], v[122:123], v[126:127]
	v_cvt_f32_i32_e32 v38, v38
	v_pk_add_f32 v[220:221], v[220:221], 1.0 op_sel_hi:[1,0]
	v_rcp_f32_e32 v128, v220
	v_cvt_f32_i32_e32 v41, v41
	v_cvt_f32_i32_e32 v40, v40
	v_cvt_f32_i32_e32 v31, v31
	v_rcp_f32_e32 v129, v221
	v_mul_f32_e32 v0, v136, v233
	v_pk_mul_f32 v[102:103], v[0:1], v[102:103] op_sel_hi:[0,1]
	v_pk_mul_f32 v[104:105], v[0:1], v[104:105] op_sel_hi:[0,1]
	v_pk_mul_f32 v[124:125], v[124:125], v[128:129]
	v_pk_mul_f32 v[98:99], v[0:1], v[98:99] op_sel_hi:[0,1]
	v_pk_mul_f32 v[124:125], v[116:117], v[124:125]
	v_pk_mul_f32 v[116:117], v[114:115], v[122:123]
	v_cvt_pk_bf16_f32 v114, v118, v119
	v_cvt_pk_bf16_f32 v115, v120, v121
	v_pk_mul_f32 v[100:101], v[0:1], v[100:101] op_sel_hi:[0,1]
	v_cvt_pk_bf16_f32 v116, v116, v117
	v_cvt_pk_bf16_f32 v117, v124, v125
	global_store_dwordx4 v152, v[114:117], s[24:25]
	v_cvt_f32_i32_e32 v30, v30
	v_cvt_f32_i32_e32 v33, v33
	v_cvt_f32_i32_e32 v117, v111
	v_cvt_f32_i32_e32 v116, v110
	v_mul_f32_e32 v114, v136, v232
	v_cvt_f32_i32_e32 v111, v113
	v_cvt_f32_i32_e32 v110, v112
	v_pk_mul_f32 v[112:113], v[114:115], v[116:117] op_sel_hi:[0,1]
	v_pk_mul_f32 v[222:223], v[112:113], s[100:101] op_sel_hi:[1,0]
	v_exp_f32_e32 v222, v222
	v_exp_f32_e32 v223, v223
	v_pk_mul_f32 v[110:111], v[114:115], v[110:111] op_sel_hi:[0,1]
	v_pk_mul_f32 v[106:107], v[114:115], v[106:107] op_sel_hi:[0,1]
	v_pk_mul_f32 v[108:109], v[114:115], v[108:109] op_sel_hi:[0,1]
	v_pk_add_f32 v[222:223], v[222:223], 1.0 op_sel_hi:[1,0]
	v_rcp_f32_e32 v116, v222
	s_add_u32 s24, s24, s98
	s_addc_u32 s25, s25, 0
	v_cvt_f32_i32_e32 v32, v32
	v_rcp_f32_e32 v117, v223
	v_pk_mul_f32 v[224:225], v[110:111], s[100:101] op_sel_hi:[1,0]
	v_exp_f32_e32 v224, v224
	v_exp_f32_e32 v225, v225
	v_cvt_f32_i32_e32 v27, v27
	v_pk_mul_f32 v[112:113], v[112:113], v[116:117]
	v_cvt_f32_i32_e32 v26, v26
	v_pk_add_f32 v[224:225], v[224:225], 1.0 op_sel_hi:[1,0]
	v_rcp_f32_e32 v118, v224
	v_pk_mul_f32 v[102:103], v[102:103], v[112:113]
	v_cvt_f32_i32_e32 v29, v29
	v_cvt_f32_i32_e32 v28, v28
	v_rcp_f32_e32 v119, v225
	v_pk_mul_f32 v[226:227], v[106:107], s[100:101] op_sel_hi:[1,0]
	v_exp_f32_e32 v226, v226
	v_exp_f32_e32 v227, v227
	v_cvt_f32_i32_e32 v37, v37
	v_pk_mul_f32 v[110:111], v[110:111], v[118:119]
	v_cvt_f32_i32_e32 v36, v36
	v_pk_add_f32 v[226:227], v[226:227], 1.0 op_sel_hi:[1,0]
	v_pk_mul_f32 v[104:105], v[104:105], v[110:111]
	v_rcp_f32_e32 v110, v226
	v_cvt_f32_i32_e32 v35, v35
	v_cvt_f32_i32_e32 v34, v34
	v_cvt_f32_i32_e32 v23, v23
	v_rcp_f32_e32 v111, v227
	v_pk_mul_f32 v[228:229], v[108:109], s[100:101] op_sel_hi:[1,0]
	v_exp_f32_e32 v228, v228
	v_exp_f32_e32 v229, v229
	v_cvt_f32_i32_e32 v22, v22
	v_pk_mul_f32 v[106:107], v[106:107], v[110:111]
	v_cvt_f32_i32_e32 v25, v25
	v_pk_add_f32 v[228:229], v[228:229], 1.0 op_sel_hi:[1,0]
	v_rcp_f32_e32 v112, v228
	v_cvt_f32_i32_e32 v24, v24
	v_cvt_f32_i32_e32 v15, v15
	v_cvt_f32_i32_e32 v14, v14
	v_rcp_f32_e32 v113, v229
	v_mul_f32_e32 v0, v137, v232
	v_pk_mul_f32 v[94:95], v[0:1], v[94:95] op_sel_hi:[0,1]
	v_pk_mul_f32 v[96:97], v[0:1], v[96:97] op_sel_hi:[0,1]
	v_pk_mul_f32 v[92:93], v[0:1], v[92:93] op_sel_hi:[0,1]
	v_pk_mul_f32 v[90:91], v[0:1], v[90:91] op_sel_hi:[0,1]
	v_pk_mul_f32 v[214:215], v[94:95], s[100:101] op_sel_hi:[1,0]
	v_exp_f32_e32 v214, v214
	v_exp_f32_e32 v215, v215
	v_pk_mul_f32 v[108:109], v[108:109], v[112:113]
	v_cvt_f32_i32_e32 v17, v17
	v_pk_mul_f32 v[108:109], v[100:101], v[108:109]
	v_pk_mul_f32 v[100:101], v[98:99], v[106:107]
	v_cvt_pk_bf16_f32 v98, v102, v103
	v_cvt_pk_bf16_f32 v99, v104, v105
	v_pk_add_f32 v[214:215], v[214:215], 1.0 op_sel_hi:[1,0]
	v_cvt_pk_bf16_f32 v100, v100, v101
	v_cvt_pk_bf16_f32 v101, v108, v109
	global_store_dwordx4 v152, v[98:101], s[24:25]
	v_cvt_f32_i32_e32 v16, v16
	v_cvt_f32_i32_e32 v11, v11
	v_rcp_f32_e32 v100, v214
	v_mul_f32_e32 v98, v137, v233
	v_pk_mul_f32 v[86:87], v[98:99], v[86:87] op_sel_hi:[0,1]
	v_rcp_f32_e32 v101, v215
	v_pk_mul_f32 v[216:217], v[96:97], s[100:101] op_sel_hi:[1,0]
	v_exp_f32_e32 v216, v216
	v_exp_f32_e32 v217, v217
	v_pk_mul_f32 v[88:89], v[98:99], v[88:89] op_sel_hi:[0,1]
	v_pk_mul_f32 v[94:95], v[94:95], v[100:101]
	v_pk_mul_f32 v[82:83], v[98:99], v[82:83] op_sel_hi:[0,1]
	v_pk_add_f32 v[216:217], v[216:217], 1.0 op_sel_hi:[1,0]
	v_rcp_f32_e32 v102, v216
	v_pk_mul_f32 v[86:87], v[86:87], v[94:95]
	v_pk_mul_f32 v[84:85], v[98:99], v[84:85] op_sel_hi:[0,1]
	s_add_u32 s24, s24, s98
	s_addc_u32 s25, s25, 0
	v_rcp_f32_e32 v103, v217
	v_pk_mul_f32 v[218:219], v[90:91], s[100:101] op_sel_hi:[1,0]
	v_exp_f32_e32 v218, v218
	v_exp_f32_e32 v219, v219
	v_cvt_f32_i32_e32 v10, v10
	v_pk_mul_f32 v[96:97], v[96:97], v[102:103]
	v_cvt_f32_i32_e32 v13, v13
	v_pk_add_f32 v[218:219], v[218:219], 1.0 op_sel_hi:[1,0]
	v_rcp_f32_e32 v94, v218
	v_pk_mul_f32 v[88:89], v[88:89], v[96:97]
	v_cvt_f32_i32_e32 v12, v12
	v_cvt_f32_i32_e32 v21, v21
	v_rcp_f32_e32 v95, v219
	v_pk_mul_f32 v[220:221], v[92:93], s[100:101] op_sel_hi:[1,0]
	v_exp_f32_e32 v220, v220
	v_exp_f32_e32 v221, v221
	v_cvt_f32_i32_e32 v20, v20
	v_pk_mul_f32 v[90:91], v[90:91], v[94:95]
	v_cvt_f32_i32_e32 v19, v19
	v_pk_add_f32 v[220:221], v[220:221], 1.0 op_sel_hi:[1,0]
	v_rcp_f32_e32 v96, v220
	v_cvt_f32_i32_e32 v18, v18
	v_cvt_f32_i32_e32 v7, v7
	v_cvt_f32_i32_e32 v6, v6
	v_rcp_f32_e32 v97, v221
	v_mul_f32_e32 v0, v138, v232
	v_pk_mul_f32 v[78:79], v[0:1], v[78:79] op_sel_hi:[0,1]
	v_pk_mul_f32 v[80:81], v[0:1], v[80:81] op_sel_hi:[0,1]
	v_pk_mul_f32 v[76:77], v[0:1], v[76:77] op_sel_hi:[0,1]
	v_pk_mul_f32 v[74:75], v[0:1], v[74:75] op_sel_hi:[0,1]
	v_pk_mul_f32 v[222:223], v[78:79], s[100:101] op_sel_hi:[1,0]
	v_exp_f32_e32 v222, v222
	v_exp_f32_e32 v223, v223
	v_pk_mul_f32 v[92:93], v[92:93], v[96:97]
	v_cvt_f32_i32_e32 v9, v9
	v_pk_mul_f32 v[92:93], v[84:85], v[92:93]
	v_pk_mul_f32 v[84:85], v[82:83], v[90:91]
	v_cvt_pk_bf16_f32 v82, v86, v87
	v_cvt_pk_bf16_f32 v83, v88, v89
	v_pk_add_f32 v[222:223], v[222:223], 1.0 op_sel_hi:[1,0]
	v_cvt_pk_bf16_f32 v84, v84, v85
	v_cvt_pk_bf16_f32 v85, v92, v93
	global_store_dwordx4 v152, v[82:85], s[24:25]
	v_cvt_f32_i32_e32 v8, v8
	v_cvt_f32_i32_e32 v5, v5
	v_rcp_f32_e32 v84, v222
	v_mul_f32_e32 v82, v138, v233
	v_pk_mul_f32 v[70:71], v[82:83], v[70:71] op_sel_hi:[0,1]
	v_rcp_f32_e32 v85, v223
	v_pk_mul_f32 v[224:225], v[80:81], s[100:101] op_sel_hi:[1,0]
	v_exp_f32_e32 v224, v224
	v_exp_f32_e32 v225, v225
	v_pk_mul_f32 v[72:73], v[82:83], v[72:73] op_sel_hi:[0,1]
	v_pk_mul_f32 v[78:79], v[78:79], v[84:85]
	v_pk_mul_f32 v[66:67], v[82:83], v[66:67] op_sel_hi:[0,1]
	v_pk_add_f32 v[224:225], v[224:225], 1.0 op_sel_hi:[1,0]
	v_rcp_f32_e32 v86, v224
	v_pk_mul_f32 v[70:71], v[70:71], v[78:79]
	v_pk_mul_f32 v[68:69], v[82:83], v[68:69] op_sel_hi:[0,1]
	s_add_u32 s24, s24, s98
	s_addc_u32 s25, s25, 0
	v_rcp_f32_e32 v87, v225
	v_pk_mul_f32 v[226:227], v[74:75], s[100:101] op_sel_hi:[1,0]
	v_exp_f32_e32 v226, v226
	v_exp_f32_e32 v227, v227
	v_cvt_f32_i32_e32 v4, v4
	v_pk_mul_f32 v[80:81], v[80:81], v[86:87]
	v_cvt_f32_i32_e32 v3, v3
	v_pk_add_f32 v[226:227], v[226:227], 1.0 op_sel_hi:[1,0]
	v_rcp_f32_e32 v78, v226
	v_pk_mul_f32 v[72:73], v[72:73], v[80:81]
	v_cvt_f32_i32_e32 v2, v2
	s_andn2_b64 vcc, exec, s[22:23]
	v_rcp_f32_e32 v79, v227
	v_pk_mul_f32 v[228:229], v[76:77], s[100:101] op_sel_hi:[1,0]
	v_exp_f32_e32 v228, v228
	v_exp_f32_e32 v229, v229
	v_pk_mul_f32 v[74:75], v[74:75], v[78:79]
	v_pk_add_f32 v[228:229], v[228:229], 1.0 op_sel_hi:[1,0]
	v_rcp_f32_e32 v80, v228
	s_nop 0
	v_rcp_f32_e32 v81, v229
	v_mul_f32_e32 v0, v139, v232
	v_pk_mul_f32 v[62:63], v[0:1], v[62:63] op_sel_hi:[0,1]
	v_pk_mul_f32 v[64:65], v[0:1], v[64:65] op_sel_hi:[0,1]
	v_pk_mul_f32 v[60:61], v[0:1], v[60:61] op_sel_hi:[0,1]
	v_pk_mul_f32 v[58:59], v[0:1], v[58:59] op_sel_hi:[0,1]
	v_pk_mul_f32 v[214:215], v[62:63], s[100:101] op_sel_hi:[1,0]
	v_exp_f32_e32 v214, v214
	v_exp_f32_e32 v215, v215
	v_pk_mul_f32 v[76:77], v[76:77], v[80:81]
	v_pk_add_f32 v[214:215], v[214:215], 1.0 op_sel_hi:[1,0]
	v_pk_mul_f32 v[76:77], v[68:69], v[76:77]
	v_pk_mul_f32 v[68:69], v[66:67], v[74:75]
	v_cvt_pk_bf16_f32 v66, v70, v71
	v_cvt_pk_bf16_f32 v67, v72, v73
	s_nop 0
	v_cvt_pk_bf16_f32 v68, v68, v69
	v_cvt_pk_bf16_f32 v69, v76, v77
	global_store_dwordx4 v152, v[66:69], s[24:25]
	s_nop 1
	v_rcp_f32_e32 v68, v214
	v_mul_f32_e32 v66, v139, v233
	v_pk_mul_f32 v[54:55], v[66:67], v[54:55] op_sel_hi:[0,1]
	v_rcp_f32_e32 v69, v215
	v_pk_mul_f32 v[216:217], v[64:65], s[100:101] op_sel_hi:[1,0]
	v_exp_f32_e32 v216, v216
	v_exp_f32_e32 v217, v217
	v_pk_mul_f32 v[56:57], v[66:67], v[56:57] op_sel_hi:[0,1]
	v_pk_mul_f32 v[62:63], v[62:63], v[68:69]
	v_pk_mul_f32 v[50:51], v[66:67], v[50:51] op_sel_hi:[0,1]
	v_pk_add_f32 v[216:217], v[216:217], 1.0 op_sel_hi:[1,0]
	v_rcp_f32_e32 v70, v216
	v_pk_mul_f32 v[54:55], v[54:55], v[62:63]
	v_pk_mul_f32 v[52:53], v[66:67], v[52:53] op_sel_hi:[0,1]
	s_add_u32 s24, s24, s99
	s_addc_u32 s25, s25, 0
	v_rcp_f32_e32 v71, v217
	v_pk_mul_f32 v[218:219], v[58:59], s[100:101] op_sel_hi:[1,0]
	v_exp_f32_e32 v218, v218
	v_exp_f32_e32 v219, v219
	v_pk_mul_f32 v[64:65], v[64:65], v[70:71]
	s_nop 0
	v_pk_mul_f32 v[56:57], v[56:57], v[64:65]
	v_pk_add_f32 v[218:219], v[218:219], 1.0 op_sel_hi:[1,0]
	v_rcp_f32_e32 v62, v218
	s_nop 0
	v_rcp_f32_e32 v63, v219
	v_pk_mul_f32 v[220:221], v[60:61], s[100:101] op_sel_hi:[1,0]
	v_exp_f32_e32 v220, v220
	v_exp_f32_e32 v221, v221
	v_pk_mul_f32 v[58:59], v[58:59], v[62:63]
	v_pk_add_f32 v[220:221], v[220:221], 1.0 op_sel_hi:[1,0]
	v_rcp_f32_e32 v64, v220
	s_nop 0
	v_rcp_f32_e32 v65, v221
	v_mul_f32_e32 v0, v140, v232
	v_pk_mul_f32 v[46:47], v[0:1], v[46:47] op_sel_hi:[0,1]
	v_pk_mul_f32 v[48:49], v[0:1], v[48:49] op_sel_hi:[0,1]
	v_pk_mul_f32 v[44:45], v[0:1], v[44:45] op_sel_hi:[0,1]
	v_pk_mul_f32 v[42:43], v[0:1], v[42:43] op_sel_hi:[0,1]
	v_pk_mul_f32 v[222:223], v[46:47], s[100:101] op_sel_hi:[1,0]
	v_exp_f32_e32 v222, v222
	v_exp_f32_e32 v223, v223
	v_pk_mul_f32 v[60:61], v[60:61], v[64:65]
	v_pk_add_f32 v[222:223], v[222:223], 1.0 op_sel_hi:[1,0]
	v_pk_mul_f32 v[60:61], v[52:53], v[60:61]
	v_pk_mul_f32 v[52:53], v[50:51], v[58:59]
	v_cvt_pk_bf16_f32 v50, v54, v55
	v_cvt_pk_bf16_f32 v51, v56, v57
	s_nop 0
	v_cvt_pk_bf16_f32 v52, v52, v53
	v_cvt_pk_bf16_f32 v53, v60, v61
	global_store_dwordx4 v152, v[50:53], s[24:25]
	s_nop 1
	v_rcp_f32_e32 v52, v222
	v_mul_f32_e32 v50, v140, v233
	v_pk_mul_f32 v[38:39], v[50:51], v[38:39] op_sel_hi:[0,1]
	v_rcp_f32_e32 v53, v223
	v_pk_mul_f32 v[224:225], v[48:49], s[100:101] op_sel_hi:[1,0]
	v_exp_f32_e32 v224, v224
	v_exp_f32_e32 v225, v225
	v_pk_mul_f32 v[40:41], v[50:51], v[40:41] op_sel_hi:[0,1]
	v_pk_mul_f32 v[46:47], v[46:47], v[52:53]
	v_pk_mul_f32 v[34:35], v[50:51], v[34:35] op_sel_hi:[0,1]
	v_pk_add_f32 v[224:225], v[224:225], 1.0 op_sel_hi:[1,0]
	v_rcp_f32_e32 v54, v224
	v_pk_mul_f32 v[38:39], v[38:39], v[46:47]
	v_pk_mul_f32 v[36:37], v[50:51], v[36:37] op_sel_hi:[0,1]
	s_add_u32 s24, s24, s98
	s_addc_u32 s25, s25, 0
	v_rcp_f32_e32 v55, v225
	v_pk_mul_f32 v[226:227], v[42:43], s[100:101] op_sel_hi:[1,0]
	v_exp_f32_e32 v226, v226
	v_exp_f32_e32 v227, v227
	v_pk_mul_f32 v[48:49], v[48:49], v[54:55]
	s_nop 0
	v_pk_mul_f32 v[40:41], v[40:41], v[48:49]
	v_pk_add_f32 v[226:227], v[226:227], 1.0 op_sel_hi:[1,0]
	v_rcp_f32_e32 v46, v226
	s_nop 0
	v_rcp_f32_e32 v47, v227
	v_pk_mul_f32 v[228:229], v[44:45], s[100:101] op_sel_hi:[1,0]
	v_exp_f32_e32 v228, v228
	v_exp_f32_e32 v229, v229
	v_pk_mul_f32 v[42:43], v[42:43], v[46:47]
	v_pk_add_f32 v[228:229], v[228:229], 1.0 op_sel_hi:[1,0]
	v_rcp_f32_e32 v48, v228
	s_nop 0
	v_rcp_f32_e32 v49, v229
	v_mul_f32_e32 v0, v141, v232
	v_pk_mul_f32 v[30:31], v[0:1], v[30:31] op_sel_hi:[0,1]
	v_pk_mul_f32 v[32:33], v[0:1], v[32:33] op_sel_hi:[0,1]
	v_pk_mul_f32 v[28:29], v[0:1], v[28:29] op_sel_hi:[0,1]
	v_pk_mul_f32 v[26:27], v[0:1], v[26:27] op_sel_hi:[0,1]
	v_pk_mul_f32 v[214:215], v[30:31], s[100:101] op_sel_hi:[1,0]
	v_exp_f32_e32 v214, v214
	v_exp_f32_e32 v215, v215
	v_pk_mul_f32 v[44:45], v[44:45], v[48:49]
	v_pk_add_f32 v[214:215], v[214:215], 1.0 op_sel_hi:[1,0]
	v_pk_mul_f32 v[44:45], v[36:37], v[44:45]
	v_pk_mul_f32 v[36:37], v[34:35], v[42:43]
	v_cvt_pk_bf16_f32 v34, v38, v39
	v_cvt_pk_bf16_f32 v35, v40, v41
	s_nop 0
	v_cvt_pk_bf16_f32 v36, v36, v37
	v_cvt_pk_bf16_f32 v37, v44, v45
	global_store_dwordx4 v152, v[34:37], s[24:25]
	s_nop 1
	v_rcp_f32_e32 v36, v214
	v_mul_f32_e32 v34, v141, v233
	v_pk_mul_f32 v[22:23], v[34:35], v[22:23] op_sel_hi:[0,1]
	v_rcp_f32_e32 v37, v215
	v_pk_mul_f32 v[216:217], v[32:33], s[100:101] op_sel_hi:[1,0]
	v_exp_f32_e32 v216, v216
	v_exp_f32_e32 v217, v217
	v_pk_mul_f32 v[24:25], v[34:35], v[24:25] op_sel_hi:[0,1]
	v_pk_mul_f32 v[30:31], v[30:31], v[36:37]
	v_pk_mul_f32 v[18:19], v[34:35], v[18:19] op_sel_hi:[0,1]
	v_pk_add_f32 v[216:217], v[216:217], 1.0 op_sel_hi:[1,0]
	v_rcp_f32_e32 v38, v216
	v_pk_mul_f32 v[22:23], v[22:23], v[30:31]
	v_pk_mul_f32 v[20:21], v[34:35], v[20:21] op_sel_hi:[0,1]
	s_add_u32 s24, s24, s98
	s_addc_u32 s25, s25, 0
	v_rcp_f32_e32 v39, v217
	v_pk_mul_f32 v[218:219], v[26:27], s[100:101] op_sel_hi:[1,0]
	v_exp_f32_e32 v218, v218
	v_exp_f32_e32 v219, v219
	v_pk_mul_f32 v[32:33], v[32:33], v[38:39]
	s_nop 0
	v_pk_mul_f32 v[24:25], v[24:25], v[32:33]
	v_pk_add_f32 v[218:219], v[218:219], 1.0 op_sel_hi:[1,0]
	v_rcp_f32_e32 v30, v218
	s_nop 0
	v_rcp_f32_e32 v31, v219
	v_pk_mul_f32 v[220:221], v[28:29], s[100:101] op_sel_hi:[1,0]
	v_exp_f32_e32 v220, v220
	v_exp_f32_e32 v221, v221
	v_pk_mul_f32 v[26:27], v[26:27], v[30:31]
	v_pk_add_f32 v[220:221], v[220:221], 1.0 op_sel_hi:[1,0]
	v_rcp_f32_e32 v32, v220
	s_nop 0
	v_rcp_f32_e32 v33, v221
	v_mul_f32_e32 v0, v142, v232
	v_pk_mul_f32 v[14:15], v[0:1], v[14:15] op_sel_hi:[0,1]
	v_pk_mul_f32 v[16:17], v[0:1], v[16:17] op_sel_hi:[0,1]
	v_pk_mul_f32 v[12:13], v[0:1], v[12:13] op_sel_hi:[0,1]
	v_pk_mul_f32 v[10:11], v[0:1], v[10:11] op_sel_hi:[0,1]
	v_pk_mul_f32 v[222:223], v[14:15], s[100:101] op_sel_hi:[1,0]
	v_exp_f32_e32 v222, v222
	v_exp_f32_e32 v223, v223
	v_pk_mul_f32 v[28:29], v[28:29], v[32:33]
	v_pk_add_f32 v[222:223], v[222:223], 1.0 op_sel_hi:[1,0]
	v_pk_mul_f32 v[28:29], v[20:21], v[28:29]
	v_pk_mul_f32 v[20:21], v[18:19], v[26:27]
	v_cvt_pk_bf16_f32 v18, v22, v23
	v_cvt_pk_bf16_f32 v19, v24, v25
	s_nop 0
	v_cvt_pk_bf16_f32 v20, v20, v21
	v_cvt_pk_bf16_f32 v21, v28, v29
	global_store_dwordx4 v152, v[18:21], s[24:25]
	s_nop 1
	v_rcp_f32_e32 v20, v222
	v_mul_f32_e32 v18, v142, v233
	v_pk_mul_f32 v[6:7], v[18:19], v[6:7] op_sel_hi:[0,1]
	v_rcp_f32_e32 v21, v223
	v_pk_mul_f32 v[224:225], v[16:17], s[100:101] op_sel_hi:[1,0]
	v_exp_f32_e32 v224, v224
	v_exp_f32_e32 v225, v225
	v_pk_mul_f32 v[8:9], v[18:19], v[8:9] op_sel_hi:[0,1]
	v_pk_mul_f32 v[14:15], v[14:15], v[20:21]
	v_pk_mul_f32 v[2:3], v[18:19], v[2:3] op_sel_hi:[0,1]
	v_pk_add_f32 v[224:225], v[224:225], 1.0 op_sel_hi:[1,0]
	v_rcp_f32_e32 v22, v224
	v_pk_mul_f32 v[6:7], v[6:7], v[14:15]
	v_pk_mul_f32 v[4:5], v[18:19], v[4:5] op_sel_hi:[0,1]
	s_add_u32 s98, s24, s98
	s_addc_u32 s99, s25, 0
	v_rcp_f32_e32 v23, v225
	v_pk_mul_f32 v[226:227], v[10:11], s[100:101] op_sel_hi:[1,0]
	v_exp_f32_e32 v226, v226
	v_exp_f32_e32 v227, v227
	s_mov_b64 s[24:25], -1
	v_pk_mul_f32 v[16:17], v[16:17], v[22:23]
	v_pk_add_f32 v[226:227], v[226:227], 1.0 op_sel_hi:[1,0]
	v_rcp_f32_e32 v14, v226
	v_pk_mul_f32 v[8:9], v[8:9], v[16:17]
	v_rcp_f32_e32 v15, v227
	v_pk_mul_f32 v[228:229], v[12:13], s[100:101] op_sel_hi:[1,0]
	v_exp_f32_e32 v228, v228
	v_exp_f32_e32 v229, v229
	v_pk_mul_f32 v[10:11], v[10:11], v[14:15]
	v_pk_add_f32 v[228:229], v[228:229], 1.0 op_sel_hi:[1,0]
	v_rcp_f32_e32 v16, v228
	s_nop 0
	v_rcp_f32_e32 v17, v229
	s_nop 0
	v_pk_mul_f32 v[12:13], v[12:13], v[16:17]
	s_nop 0
	v_pk_mul_f32 v[12:13], v[4:5], v[12:13]
	v_pk_mul_f32 v[4:5], v[2:3], v[10:11]
	v_cvt_pk_bf16_f32 v2, v6, v7
	v_cvt_pk_bf16_f32 v3, v8, v9
	s_nop 0
	v_cvt_pk_bf16_f32 v4, v4, v5
	v_cvt_pk_bf16_f32 v5, v12, v13
	global_store_dwordx4 v152, v[2:5], s[98:99]
	s_cbranch_vccnz .LBB0_441
	s_cmp_eq_u32 s83, s71
	s_cbranch_scc1 .LBB0_451
	v_lshl_add_u32 v2, s83, 8, v146
	v_ashrrev_i32_e32 v3, 31, v2
	v_lshl_add_u64 v[2:3], v[2:3], 2, s[4:5]
	global_load_dword v135, v[2:3], off sc1
	global_load_dword v136, v[2:3], off offset:64 sc1
	global_load_dword v137, v[2:3], off offset:128 sc1
	global_load_dword v138, v[2:3], off offset:192 sc1
	global_load_dword v139, v[2:3], off offset:512 sc1
	global_load_dword v140, v[2:3], off offset:576 sc1
	global_load_dword v141, v[2:3], off offset:640 sc1
	global_load_dword v142, v[2:3], off offset:704 sc1

.LBB0_1314:
	v_lshlrev_b32_e32 v0, 1, v216
	v_and_b32_e32 v223, 32, v0
	v_lshrrev_b32_e32 v0, 2, v216
	v_and_or_b32 v0, v0, 3, v221
	v_lshlrev_b32_e32 v222, 6, v0
	v_add_u32_e32 v0, 0, v223
	v_add3_u32 v240, v0, v220, v222
	v_max3_f32 v0, v2, v3, v18
	v_max3_f32 v34, v4, v5, v19
	s_lshl_b32 s71, s24, 8
	v_max3_f32 v0, v0, v20, v21
	v_max3_f32 v34, v34, v8, v9
	s_and_b32 s17, s17, 0x3fffffc0
	v_max3_f32 v0, v0, v6, v7
	v_max3_f32 v34, v34, v24, v25
	s_add_i32 s76, s71, 0x100
	v_max3_f32 v0, v0, v22, v23
	v_max3_f32 v34, v34, v12, v13
	s_lshl_b32 s17, s17, 2
	v_max3_f32 v0, v0, v10, v11
	v_max3_f32 v34, v34, v28, v29
	s_add_i32 s17, s17, 0
	v_max3_f32 v0, v0, v26, v27
	v_max3_f32 v34, v34, v16, v17
	s_lshr_b32 s77, s76, 6
	v_max3_f32 v0, v0, v14, v15
	v_max3_f32 v34, v34, v32, v33
	s_mov_b64 s[22:23], 0x30000
	v_max3_f32 v0, v0, v30, v31
	s_cmp_lg_u32 0, -1
	v_max_f32_e32 v0, v0, v34
	s_mov_b32 s50, 1
	v_mov_b32_e32 v34, v0
	s_nop 1
	v_permlane32_swap_b32_e32 v0, v34
	v_max_f32_e32 v0, v0, v34
	s_mov_b32 s25, 0
	v_add_f32_e32 v229, v1, v0
	v_sub_f32_e32 v2, v2, v0
	v_sub_f32_e32 v3, v3, v0
	v_sub_f32_e32 v18, v18, v0
	v_sub_f32_e32 v19, v19, v0
	v_sub_f32_e32 v4, v4, v0
	s_nop 0
	v_xor_b32_e32 v48, 0x80000000, v229
	v_mov_b32_e32 v49, v48
	v_mov_b32_e32 v50, v48
	v_mov_b32_e32 v51, v48
	v_mov_b32_e32 v52, v48
	v_mov_b32_e32 v53, v48
	v_mov_b32_e32 v54, v48
	v_mov_b32_e32 v55, v48
	v_mov_b32_e32 v56, v48
	v_mov_b32_e32 v57, v48
	v_mov_b32_e32 v58, v48
	v_mov_b32_e32 v59, v48
	v_mov_b32_e32 v60, v48
	v_mov_b32_e32 v61, v48
	v_mov_b32_e32 v62, v48
	v_mov_b32_e32 v63, v48
	s_waitcnt vmcnt(0) lgkmcnt(0)
	s_barrier
	v_exp_f32_e32 v80, v2
	v_exp_f32_e32 v81, v3
	v_lshl_add_u64 v[2:3], v[212:213], 0, s[22:23]
	s_mov_b32 s22, m0
	s_mov_b32 m0, s74
	s_nop 0
	global_load_lds_dwordx4 v[2:3], off
	s_mov_b32 m0, s22
	s_cselect_b32 s22, 0, 0
	s_add_i32 s16, s22, s16
	v_lshl_add_u64 v[2:3], v[214:215], 0, s[30:31]
	s_add_i32 s16, s16, 0x8000
	s_mov_b32 s22, m0
	s_mov_b32 m0, s16
	s_nop 0
	global_load_lds_dwordx4 v[2:3], off
	s_mov_b32 m0, s22
	ds_read_b128 v[188:191], v228 offset:8192
	ds_read_b128 v[184:187], v228 offset:8704
	ds_read_b128 v[180:183], v228 offset:10240
	ds_read_b128 v[176:179], v228 offset:10752
	ds_read_b128 v[172:175], v228 offset:12288
	ds_read_b128 v[168:171], v228 offset:12800
	ds_read_b128 v[164:167], v228 offset:14336
	ds_read_b128 v[160:163], v228 offset:14848
	v_sub_f32_e32 v20, v20, v0
	v_sub_f32_e32 v5, v5, v0
	v_sub_f32_e32 v21, v21, v0
	v_sub_f32_e32 v6, v6, v0
	v_sub_f32_e32 v22, v22, v0
	v_sub_f32_e32 v7, v7, v0
	v_sub_f32_e32 v23, v23, v0
	v_sub_f32_e32 v8, v8, v0
	v_sub_f32_e32 v24, v24, v0
	v_sub_f32_e32 v9, v9, v0
	v_sub_f32_e32 v25, v25, v0
	v_sub_f32_e32 v10, v10, v0
	v_sub_f32_e32 v26, v26, v0
	v_sub_f32_e32 v11, v11, v0
	v_sub_f32_e32 v27, v27, v0
	v_sub_f32_e32 v12, v12, v0
	v_sub_f32_e32 v28, v28, v0
	v_sub_f32_e32 v13, v13, v0
	v_sub_f32_e32 v29, v29, v0
	v_sub_f32_e32 v14, v14, v0
	v_sub_f32_e32 v30, v30, v0
	v_sub_f32_e32 v15, v15, v0
	v_sub_f32_e32 v31, v31, v0
	v_sub_f32_e32 v16, v16, v0
	v_sub_f32_e32 v32, v32, v0
	v_sub_f32_e32 v17, v17, v0
	v_sub_f32_e32 v0, v33, v0
	v_exp_f32_e32 v82, v4
	v_exp_f32_e32 v83, v5
	v_exp_f32_e32 v84, v6
	v_exp_f32_e32 v85, v7
	v_exp_f32_e32 v86, v8
	v_exp_f32_e32 v87, v9
	v_exp_f32_e32 v88, v10
	v_exp_f32_e32 v89, v11
	v_exp_f32_e32 v90, v12
	v_exp_f32_e32 v91, v13
	v_exp_f32_e32 v92, v14
	v_exp_f32_e32 v93, v15
	v_exp_f32_e32 v94, v16
	v_exp_f32_e32 v95, v17
	v_exp_f32_e32 v64, v18
	v_exp_f32_e32 v65, v19
	v_exp_f32_e32 v66, v20
	v_exp_f32_e32 v67, v21
	v_exp_f32_e32 v68, v22
	v_exp_f32_e32 v69, v23
	v_exp_f32_e32 v70, v24
	v_exp_f32_e32 v71, v25
	v_exp_f32_e32 v72, v26
	v_exp_f32_e32 v73, v27
	v_exp_f32_e32 v74, v28
	v_exp_f32_e32 v75, v29
	v_exp_f32_e32 v76, v30
	v_exp_f32_e32 v77, v31
	v_exp_f32_e32 v78, v32
	v_exp_f32_e32 v79, v0
	s_waitcnt vmcnt(2) lgkmcnt(0)
	s_barrier
	s_andn2_b64 vcc, exec, s[2:3]
	v_cmp_gt_u32_e64 s[2:3], 32, v217
	v_lshl_add_u32 v226, v218, 2, s17
	v_lshl_add_u32 v224, v221, 2, s17
	s_cbranch_vccnz .LBB0_1330
	v_mov_b32_e32 v14, v1
	v_mov_b32_e32 v15, v1
	v_readlane_b32 s16, v255, 9
	v_mov_b32_e32 v0, v1
	v_mov_b32_e32 v2, v1
	v_mov_b32_e32 v3, v1
	v_mov_b32_e32 v4, v1
	v_mov_b32_e32 v5, v1
	v_mov_b32_e32 v6, v1
	v_mov_b32_e32 v7, v1
	v_mov_b32_e32 v8, v1
	v_mov_b32_e32 v9, v1
	v_mov_b32_e32 v10, v1
	v_mov_b32_e32 v11, v1
	v_mov_b32_e32 v12, v1
	v_mov_b32_e32 v13, v1
	v_mov_b64_e32 v[46:47], v[14:15]
	v_mov_b64_e32 v[30:31], v[14:15]
	v_lshl_add_u32 v200, v219, 4, s16
	v_readfirstlane_b32 s98, v212
	v_readfirstlane_b32 s99, v213
	s_nop 1
	v_subrev_u32_e32 v236, s98, v212
	v_subrev_u32_e32 v237, s98, v214
	s_mov_b32 s16, 0
	s_movk_i32 s25, 0x4000
	s_movk_i32 s50, 0x2000
	v_mov_b32_e32 v241, 0
	s_mov_b32 s46, 6
	s_mov_b32 s47, 0x20000
	v_mov_b64_e32 v[44:45], v[12:13]
	v_mov_b64_e32 v[42:43], v[10:11]
	v_mov_b64_e32 v[40:41], v[8:9]
	v_mov_b64_e32 v[38:39], v[6:7]
	v_mov_b64_e32 v[36:37], v[4:5]
	v_mov_b64_e32 v[34:35], v[2:3]
	v_mov_b64_e32 v[32:33], v[0:1]
	v_mov_b64_e32 v[28:29], v[12:13]
	v_mov_b64_e32 v[26:27], v[10:11]
	v_mov_b64_e32 v[24:25], v[8:9]
	v_mov_b64_e32 v[22:23], v[6:7]
	v_mov_b64_e32 v[20:21], v[4:5]
	v_mov_b64_e32 v[18:19], v[2:3]
	v_mov_b64_e32 v[16:17], v[0:1]
	.p2align	6
